# v30_chunk32
# speedup vs baseline: 1.0013x; 1.0013x over previous
; __device__ void attn_item(const Params& p, int id) {
;     ...
;   const int g = id >> 10, rem = id & 1023, h = rem & 7, tb = rem >> 3;
;   int seq, local;
;   if (tb < 64) { seq = tb >> 4; local = tb & 15; } else { seq = 4; local = tb - 64; }
;   const int dsh = g * 2, d = 1 << dsh;
;   const int start = seq_start(seq), len = seq_len(seq), L = len >> dsh, nub = L >> 7;
;   const int r = local / nub, ub = local % nub, u0 = ub * 128;
; __device__ void phase2(const Params& p, const int rep) {
;     ...
;     if (threadIdx.x == 0) *sid = atomicAdd(p.counters + rep, 1);
;     __syncthreads();
;     int id = *sid;
;     __syncthreads();
;     if (id >= 3072) break;
;     attn_item(p, 3071 - id);
.Lat_have:
	s_lshr_b32 s5, s4, 5
	s_and_b32 s4, s4, 31
	s_lshl_b32 s5, s5, 8
	s_or_b32 s4, s4, s5
	s_lshl_b32 s5, s98, 5
	s_or_b32 s4, s4, s5
	s_sub_i32 s4, 0xbff, s4
	s_bfe_u32 s6, s4, 0x70003
	s_lshr_b32 s8, s4, 10
	s_and_b32 s47, s4, 7
	v_sub_co_u32_e64 v0, s[0:1], s6, 64
	s_bfe_u32 s7, s4, 0x40003
	s_and_b64 s[4:5], s[0:1], exec
	v_readfirstlane_b32 s4, v0
	s_cselect_b32 s7, s7, s4
	s_min_u32 s4, s6, 64
	s_lshl_b32 s4, s4, 7
	s_lshl_b32 s6, s8, 1
	s_and_b32 s56, s4, 0x3800
	s_and_b64 s[4:5], s[0:1], exec
	s_cselect_b32 s4, s3, 0x2000
	s_lshr_b32 s57, s4, s6
	s_lshr_b32 s4, s57, 7
	s_and_b64 s[0:1], s[0:1], exec
	s_cselect_b32 s0, 11, 13
	s_sub_i32 s0, s0, s6
	s_add_i32 s0, s0, 0xfff9
	s_and_b32 s1, s7, 0xff
	s_add_i32 s4, s4, -1
	s_lshr_b32 s5, s1, s0
	s_and_b32 s0, s4, s7
	s_lshl_b32 s0, s0, 7
	s_and_b32 s7, s0, 0x7f80
	s_mul_i32 s0, s8, 0xc00
	s_mov_b32 s1, s9
	s_lshl_b64 s[0:1], s[0:1], 1
	s_add_u32 s0, s74, s0
	s_addc_u32 s1, s75, s1
	s_lshl_b32 s4, s47, 8
	v_mov_b32_e32 v79, v248
	s_add_u32 s0, s0, s4
	s_addc_u32 s1, s1, 0
	v_and_b32_e32 v80, 15, v79
	v_ashrrev_i32_e32 v81, 4, v79
	s_sub_i32 s4, s7, 64
	v_lshl_add_u32 v37, v81, 3, s4
	v_lshlrev_b32_e32 v64, 4, v80
	s_or_b32 s58, s56, s5
	v_lshl_add_u64 v[66:67], s[0:1], 0, v[64:65]
	v_cmp_gt_u32_e32 vcc, s57, v37
	v_mov_b32_e32 v0, 0
	v_mov_b32_e32 v4, 0
	v_mov_b32_e32 v5, 0
	v_mov_b32_e32 v6, 0
	v_mov_b32_e32 v7, 0
	v_mov_b32_e32 v16, 0
	v_mov_b32_e32 v17, 0
	v_mov_b32_e32 v18, 0
	v_mov_b32_e32 v19, 0
	s_and_saveexec_b64 s[4:5], vcc
	s_cbranch_execz .LBB0_458
	v_lshlrev_b32_e32 v1, s6, v37
	v_add_u32_e32 v2, s58, v1
	v_ashrrev_i32_e32 v3, 31, v2
	v_lshlrev_b64 v[2:3], 15, v[2:3]
	v_lshl_add_u64 v[2:3], v[66:67], 0, v[2:3]
	v_add_co_u32_e32 v4, vcc, 0x1000, v2
	s_nop 1
	v_addc_co_u32_e32 v5, vcc, 0, v3, vcc
	global_load_dwordx4 v[16:19], v[2:3], off offset:2048
	s_nop 0
	global_load_dwordx4 v[4:7], v[4:5], off
